# conv1d LayerNorm finalisation (16 threads, rest parked): 32 serialized ds_read2+lgkmcnt(0) steps batched into 2x16 reads with counted lgkmcnt waits, same add order
# speedup vs baseline: 1.0026x; 1.0026x over previous
; __device__ __forceinline__ void conv1d_phase(const Frame& F, int l, int nrows) {
;     ...
;     auto load_tile = [&](int item) {
;         const int r0 = item * TT;
;         const int slo = r0 < ML ? (r0 / SEQ) * SEQ : ML + ((r0 - ML) / CTXL) * CTXL, shi = slo + (r0 < ML ? SEQ : CTXL);
; #pragma unroll
;         for (int k = 0; k < NR / 4; ++k) {
;             const int rr = r0 - 15 + srow + 4 * k, rc = min(max(rr, slo), shi - 1); const unsigned msk = (unsigned)-(int)(rr == rc);
;             const u32x4 v = *(const u32x4*)(U + (size_t)rc * D + scol);
;             pre[k] = (u32x4){v.x & msk, v.y & msk, v.z & msk, v.w & msk};
;         }
;     };
;     ...
;         { const int nx_ = item_of(k + 1); load_tile(nx_ >= 0 ? nx_ : it); }
;         __syncthreads();
; #pragma unroll
;         for (int t = 0; t < TT; ++t) { red[(2 * t) * 512 + tid] = y[t].x + y[t].y; red[(2 * t + 1) * 512 + tid] = y[t].x * y[t].x + y[t].y * y[t].y; }
;         __syncthreads();
.LBB0_1242:
	v_add_u32_e32 v0, s8, v190
	s_add_i32 s10, s9, s0
	v_max_i32_e32 v2, s9, v0
	v_min_i32_e32 v2, s10, v2
	v_cmp_eq_u32_e64 s[6:7], v0, v2
	v_add_u32_e32 v0, s8, v191
	v_max_i32_e32 v4, s9, v0
	v_min_i32_e32 v4, s10, v4
	v_cmp_eq_u32_e64 s[0:1], v0, v4
	v_add_u32_e32 v0, s8, v192
	v_max_i32_e32 v10, s9, v0
	v_min_i32_e32 v10, s10, v10
	v_cmp_eq_u32_e64 s[2:3], v0, v10
	v_add_u32_e32 v0, s8, v193
	v_add_u32_e32 v212, s8, v195
	v_max_i32_e32 v12, s9, v0
	v_max_i32_e32 v36, s9, v212
	v_min_i32_e32 v12, s10, v12
	v_min_i32_e32 v200, s10, v36
	v_cmp_eq_u32_e64 s[4:5], v0, v12
	v_add_u32_e32 v0, s8, v138
	v_ashrrev_i32_e32 v201, 31, v200
	v_add_u32_e32 v19, 1, v0
	v_add_u32_e32 v21, 5, v0
	v_add_u32_e32 v209, 9, v0
	v_add_u32_e32 v0, 13, v0
	v_lshlrev_b64 v[36:37], 11, v[200:201]
	v_add_u32_e32 v201, s8, v196
	v_max_i32_e32 v28, s9, v0
	v_max_i32_e32 v42, s9, v201
	v_min_i32_e32 v164, s10, v28
	v_min_i32_e32 v202, s10, v42
	v_ashrrev_i32_e32 v165, 31, v164
	v_ashrrev_i32_e32 v203, 31, v202
	v_lshlrev_b64 v[28:29], 11, v[164:165]
	v_add_u32_e32 v165, s8, v194
	v_lshlrev_b64 v[42:43], 11, v[202:203]
	v_add_u32_e32 v203, s8, v197
	v_max_i32_e32 v18, s9, v19
	v_max_i32_e32 v20, s9, v21
	v_max_i32_e32 v26, s9, v209
	v_max_i32_e32 v34, s9, v165
	v_max_i32_e32 v44, s9, v203
	v_min_i32_e32 v18, s10, v18
	v_min_i32_e32 v20, s10, v20
	v_min_i32_e32 v162, s10, v26
	v_min_i32_e32 v198, s10, v34
	v_min_i32_e32 v206, s10, v44
	v_ashrrev_i32_e32 v3, 31, v2
	v_ashrrev_i32_e32 v5, 31, v4
	v_ashrrev_i32_e32 v11, 31, v10
	v_ashrrev_i32_e32 v13, 31, v12
	v_cmp_eq_u32_e64 s[88:89], v19, v18
	v_ashrrev_i32_e32 v19, 31, v18
	v_cmp_eq_u32_e64 s[72:73], v21, v20
	v_ashrrev_i32_e32 v21, 31, v20
	v_ashrrev_i32_e32 v163, 31, v162
	v_ashrrev_i32_e32 v199, 31, v198
	v_ashrrev_i32_e32 v207, 31, v206
	v_lshlrev_b64 v[2:3], 11, v[2:3]
	v_lshlrev_b64 v[4:5], 11, v[4:5]
	v_lshlrev_b64 v[10:11], 11, v[10:11]
	v_lshlrev_b64 v[12:13], 11, v[12:13]
	v_lshlrev_b64 v[18:19], 11, v[18:19]
	v_lshlrev_b64 v[20:21], 11, v[20:21]
	v_lshlrev_b64 v[26:27], 11, v[162:163]
	v_lshlrev_b64 v[34:35], 11, v[198:199]
	v_lshlrev_b64 v[44:45], 11, v[206:207]
	v_lshl_add_u64 v[2:3], v[72:73], 0, v[2:3]
	v_lshl_add_u64 v[6:7], v[72:73], 0, v[4:5]
	v_lshl_add_u64 v[10:11], v[72:73], 0, v[10:11]
	v_lshl_add_u64 v[14:15], v[72:73], 0, v[12:13]
	v_lshl_add_u64 v[18:19], v[72:73], 0, v[18:19]
	v_lshl_add_u64 v[22:23], v[72:73], 0, v[20:21]
	v_lshl_add_u64 v[26:27], v[72:73], 0, v[26:27]
	v_lshl_add_u64 v[30:31], v[72:73], 0, v[28:29]
	v_lshl_add_u64 v[34:35], v[72:73], 0, v[34:35]
	v_lshl_add_u64 v[38:39], v[72:73], 0, v[36:37]
	v_lshl_add_u64 v[42:43], v[72:73], 0, v[42:43]
	v_lshl_add_u64 v[46:47], v[72:73], 0, v[44:45]
	global_load_dwordx4 v[2:5], v[2:3], off
	s_nop 0
	global_load_dwordx4 v[6:9], v[6:7], off
	s_nop 0
	global_load_dwordx4 v[10:13], v[10:11], off
	s_nop 0
	global_load_dwordx4 v[14:17], v[14:15], off
	s_nop 0
	global_load_dwordx4 v[18:21], v[18:19], off
	s_nop 0
	global_load_dwordx4 v[22:25], v[22:23], off
	s_nop 0
	global_load_dwordx4 v[26:29], v[26:27], off
	s_nop 0
	global_load_dwordx4 v[30:33], v[30:31], off
	s_nop 0
	global_load_dwordx4 v[34:37], v[34:35], off
	s_nop 0
	global_load_dwordx4 v[38:41], v[38:39], off
	s_nop 0
	global_load_dwordx4 v[42:45], v[42:43], off
	s_nop 0
	global_load_dwordx4 v[46:49], v[46:47], off
	v_pk_mul_f32 v[210:211], v[136:137], v[136:137]
	v_add_f32_e32 v163, v136, v137
	v_add_f32_e32 v199, v210, v211
	v_pk_mul_f32 v[210:211], v[134:135], v[134:135]
	s_barrier
	ds_write2st64_b32 v140, v163, v199 offset1:8
	v_add_f32_e32 v163, v134, v135
	v_add_f32_e32 v199, v210, v211
	v_pk_mul_f32 v[210:211], v[132:133], v[132:133]
	ds_write2st64_b32 v140, v163, v199 offset0:16 offset1:24
	v_add_f32_e32 v163, v132, v133
	v_add_f32_e32 v199, v210, v211
	v_pk_mul_f32 v[210:211], v[130:131], v[130:131]
	ds_write2st64_b32 v140, v163, v199 offset0:32 offset1:40
	v_add_f32_e32 v163, v130, v131
	v_add_f32_e32 v199, v210, v211
	v_pk_mul_f32 v[210:211], v[128:129], v[128:129]
	ds_write2st64_b32 v140, v163, v199 offset0:48 offset1:56
	v_add_f32_e32 v163, v128, v129
	v_add_f32_e32 v199, v210, v211
	v_pk_mul_f32 v[210:211], v[126:127], v[126:127]
	ds_write2st64_b32 v140, v163, v199 offset0:64 offset1:72
	v_add_f32_e32 v163, v126, v127
	v_add_f32_e32 v199, v210, v211
	v_pk_mul_f32 v[210:211], v[124:125], v[124:125]
	ds_write2st64_b32 v140, v163, v199 offset0:80 offset1:88
	v_add_f32_e32 v163, v124, v125
	v_add_f32_e32 v199, v210, v211
	v_pk_mul_f32 v[210:211], v[122:123], v[122:123]
	ds_write2st64_b32 v140, v163, v199 offset0:96 offset1:104
	v_add_f32_e32 v163, v122, v123
	v_add_f32_e32 v199, v210, v211
	v_pk_mul_f32 v[210:211], v[120:121], v[120:121]
	ds_write2st64_b32 v140, v163, v199 offset0:112 offset1:120
	v_add_f32_e32 v163, v120, v121
	v_add_f32_e32 v199, v210, v211
	v_pk_mul_f32 v[210:211], v[118:119], v[118:119]
	ds_write2st64_b32 v140, v163, v199 offset0:128 offset1:136
	v_add_f32_e32 v163, v118, v119
	v_add_f32_e32 v199, v210, v211
	v_pk_mul_f32 v[210:211], v[116:117], v[116:117]
	ds_write2st64_b32 v140, v163, v199 offset0:144 offset1:152
	v_add_f32_e32 v163, v116, v117
	v_add_f32_e32 v199, v210, v211
	v_pk_mul_f32 v[210:211], v[114:115], v[114:115]
	ds_write2st64_b32 v140, v163, v199 offset0:160 offset1:168
	v_add_f32_e32 v163, v114, v115
	v_add_f32_e32 v199, v210, v211
	v_pk_mul_f32 v[210:211], v[112:113], v[112:113]
	ds_write2st64_b32 v140, v163, v199 offset0:176 offset1:184
	v_add_f32_e32 v163, v112, v113
	v_add_f32_e32 v199, v210, v211
	v_pk_mul_f32 v[210:211], v[110:111], v[110:111]
	ds_write2st64_b32 v140, v163, v199 offset0:192 offset1:200
	v_add_f32_e32 v163, v110, v111
	v_add_f32_e32 v199, v210, v211
	v_pk_mul_f32 v[210:211], v[108:109], v[108:109]
	ds_write2st64_b32 v140, v163, v199 offset0:208 offset1:216
	v_add_f32_e32 v163, v108, v109
	v_add_f32_e32 v199, v210, v211
	v_pk_mul_f32 v[210:211], v[106:107], v[106:107]
	ds_write2st64_b32 v140, v163, v199 offset0:224 offset1:232
	v_add_f32_e32 v163, v106, v107
	v_add_f32_e32 v199, v210, v211
	ds_write2st64_b32 v140, v163, v199 offset0:240 offset1:248
	s_waitcnt lgkmcnt(0)
	s_barrier
; __device__ __forceinline__ float rsqrtf_(float x) { return __builtin_amdgcn_rsqf(x); }
; __device__ __forceinline__ void conv1d_phase(const Frame& F, int l, int nrows) {
;     ...
;         {
; #pragma unroll
;             for (int rep = 0; rep < 2; ++rep) { const int o = tid + 512 * rep, st = o >> 5, part = o & 31; float sacc = 0.f;
; #pragma unroll
;                 for (int k = 0; k < 16; ++k) sacc += red[st * 512 + part + 32 * k];
;                 red2[st * 32 + part] = sacc; }
;         }
;         __syncthreads();
;         if (tid < TT) { float s1 = 0.f, s2 = 0.f;
; #pragma unroll
;             for (int k = 0; k < 32; ++k) { s1 += red2[(2 * tid) * 32 + ((k + tid) & 31)]; s2 += red2[(2 * tid + 1) * 32 + ((k + tid) & 31)]; }
;             const float mean = s1 * (1.0f / D), var = fmaxf(s2 * (1.0f / D) - mean * mean, 0.f);
;             fin[2 * tid] = mean; fin[2 * tid + 1] = rsqrtf_(var + EPS); }
	ds_read2_b32 v[210:211], v146 offset1:32
	v_cmp_eq_u32_e64 s[76:77], v209, v162
	ds_read2_b32 v[162:163], v146 offset0:64 offset1:96
	v_cmp_eq_u32_e64 s[92:93], v0, v164
	v_cmp_eq_u32_e64 s[74:75], v165, v198
	s_waitcnt lgkmcnt(1)
	v_add_f32_e32 v0, 0, v210
	ds_read2_b32 v[164:165], v146 offset0:128 offset1:160
	v_add_f32_e32 v0, v0, v211
	s_waitcnt lgkmcnt(1)
	v_add_f32_e32 v0, v0, v162
	v_add_f32_e32 v0, v0, v163
	ds_read2_b32 v[162:163], v146 offset0:192 offset1:224
	s_waitcnt lgkmcnt(1)
	v_add_f32_e32 v0, v0, v164
	v_add_u32_e32 v207, 0x400, v146
	ds_read2_b32 v[198:199], v207 offset1:32
	v_add_f32_e32 v0, v0, v165
	s_waitcnt lgkmcnt(1)
	v_add_f32_e32 v0, v0, v162
	v_add_f32_e32 v0, v0, v163
	ds_read2_b32 v[162:163], v207 offset0:64 offset1:96
	ds_read2_b32 v[164:165], v207 offset0:128 offset1:160
	s_waitcnt lgkmcnt(2)
	v_add_f32_e32 v0, v0, v198
	v_add_f32_e32 v0, v0, v199
	ds_read2_b32 v[198:199], v207 offset0:192 offset1:224
	s_waitcnt lgkmcnt(2)
	v_add_f32_e32 v0, v0, v162
	v_add_f32_e32 v0, v0, v163
	s_waitcnt lgkmcnt(1)
	v_add_f32_e32 v0, v0, v164
	v_add_f32_e32 v0, v0, v165
	s_waitcnt lgkmcnt(0)
	v_add_f32_e32 v0, v0, v198
	v_add_f32_e32 v0, v0, v199
	ds_write_b32 v147, v0
	ds_read2_b32 v[162:163], v148 offset1:32
	ds_read2_b32 v[164:165], v148 offset0:64 offset1:96
	ds_read2_b32 v[198:199], v148 offset0:128 offset1:160
	v_cmp_eq_u32_e32 vcc, v212, v200
	v_add_u32_e32 v200, 0x400, v148
	s_waitcnt lgkmcnt(2)
	v_add_f32_e32 v0, 0, v162
	v_add_f32_e32 v0, v0, v163
	ds_read2_b32 v[162:163], v148 offset0:192 offset1:224
	s_waitcnt lgkmcnt(2)
	v_add_f32_e32 v0, v0, v164
	v_add_f32_e32 v0, v0, v165
	s_waitcnt lgkmcnt(1)
	v_add_f32_e32 v0, v0, v198
	ds_read2_b32 v[164:165], v200 offset1:32
	v_add_f32_e32 v0, v0, v199
	s_waitcnt lgkmcnt(1)
	v_add_f32_e32 v0, v0, v162
	v_add_f32_e32 v0, v0, v163
	ds_read2_b32 v[162:163], v200 offset0:64 offset1:96
	ds_read2_b32 v[198:199], v200 offset0:128 offset1:160
	s_waitcnt lgkmcnt(2)
	v_add_f32_e32 v0, v0, v164
	v_add_f32_e32 v0, v0, v165
	ds_read2_b32 v[164:165], v200 offset0:192 offset1:224
	s_waitcnt lgkmcnt(2)
	v_add_f32_e32 v0, v0, v162
	v_add_f32_e32 v0, v0, v163
	s_waitcnt lgkmcnt(1)
	v_add_f32_e32 v0, v0, v198
	v_add_f32_e32 v0, v0, v199
	s_waitcnt lgkmcnt(0)
	v_add_f32_e32 v0, v0, v164
	v_cmp_eq_u32_e64 s[10:11], v201, v202
	v_cmp_eq_u32_e64 s[8:9], v203, v206
	v_add_f32_e32 v0, v0, v165
	ds_write_b32 v149, v0
	s_waitcnt lgkmcnt(0)
	s_barrier
	s_and_saveexec_b64 s[30:31], s[62:63]
	s_cbranch_execz .LBB0_1209
	s_mov_b32 s26, 0x3a800000
	ds_read2_b32 v[74:75], v150 offset1:32
	ds_read2_b32 v[76:77], v151 offset1:32
	ds_read2_b32 v[78:79], v152 offset1:32
	ds_read2_b32 v[80:81], v153 offset1:32
	ds_read2_b32 v[82:83], v154 offset1:32
	ds_read2_b32 v[84:85], v155 offset1:32
	ds_read2_b32 v[86:87], v156 offset1:32
	ds_read2_b32 v[88:89], v157 offset1:32
	ds_read2_b32 v[90:91], v158 offset1:32
	ds_read2_b32 v[92:93], v159 offset1:32
	ds_read2_b32 v[94:95], v160 offset1:32
	ds_read2_b32 v[96:97], v161 offset1:32
	ds_read2_b32 v[228:229], v170 offset1:32
	ds_read2_b32 v[230:231], v171 offset1:32
	ds_read2_b32 v[232:233], v172 offset1:32
	ds_read2_b32 v[234:235], v173 offset1:32
	s_waitcnt lgkmcnt(15)
	v_add_f32_e32 v0, 0, v74
	v_add_f32_e32 v164, 0, v75
	s_waitcnt lgkmcnt(14)
	v_add_f32_e32 v0, v0, v76
	v_add_f32_e32 v164, v164, v77
	s_waitcnt lgkmcnt(13)
	v_add_f32_e32 v0, v0, v78
	v_add_f32_e32 v164, v164, v79
	s_waitcnt lgkmcnt(12)
	v_add_f32_e32 v0, v0, v80
	v_add_f32_e32 v164, v164, v81
	s_waitcnt lgkmcnt(11)
	v_add_f32_e32 v0, v0, v82
	v_add_f32_e32 v164, v164, v83
	s_waitcnt lgkmcnt(10)
	v_add_f32_e32 v0, v0, v84
	v_add_f32_e32 v164, v164, v85
	s_waitcnt lgkmcnt(9)
	v_add_f32_e32 v0, v0, v86
	v_add_f32_e32 v164, v164, v87
	s_waitcnt lgkmcnt(8)
	v_add_f32_e32 v0, v0, v88
	v_add_f32_e32 v164, v164, v89
	s_waitcnt lgkmcnt(7)
	v_add_f32_e32 v0, v0, v90
	v_add_f32_e32 v164, v164, v91
	s_waitcnt lgkmcnt(6)
	v_add_f32_e32 v0, v0, v92
	v_add_f32_e32 v164, v164, v93
	s_waitcnt lgkmcnt(5)
	v_add_f32_e32 v0, v0, v94
	v_add_f32_e32 v164, v164, v95
	s_waitcnt lgkmcnt(4)
	v_add_f32_e32 v0, v0, v96
	v_add_f32_e32 v164, v164, v97
	s_waitcnt lgkmcnt(3)
	v_add_f32_e32 v0, v0, v228
	v_add_f32_e32 v164, v164, v229
	s_waitcnt lgkmcnt(2)
	v_add_f32_e32 v0, v0, v230
	v_add_f32_e32 v164, v164, v231
	s_waitcnt lgkmcnt(1)
	v_add_f32_e32 v0, v0, v232
	v_add_f32_e32 v164, v164, v233
	s_waitcnt lgkmcnt(0)
	v_add_f32_e32 v0, v0, v234
	v_add_f32_e32 v164, v164, v235
	ds_read2_b32 v[74:75], v174 offset1:32
	ds_read2_b32 v[76:77], v175 offset1:32
	ds_read2_b32 v[78:79], v176 offset1:32
	ds_read2_b32 v[80:81], v177 offset1:32
	ds_read2_b32 v[82:83], v178 offset1:32
	ds_read2_b32 v[84:85], v179 offset1:32
	ds_read2_b32 v[86:87], v180 offset1:32
	ds_read2_b32 v[88:89], v181 offset1:32
	ds_read2_b32 v[90:91], v182 offset1:32
	ds_read2_b32 v[92:93], v183 offset1:32
	ds_read2_b32 v[94:95], v184 offset1:32
	ds_read2_b32 v[96:97], v185 offset1:32
	ds_read2_b32 v[228:229], v186 offset1:32
	ds_read2_b32 v[230:231], v187 offset1:32
	ds_read2_b32 v[232:233], v188 offset1:32
	ds_read2_b32 v[234:235], v189 offset1:32
	s_waitcnt lgkmcnt(15)
	v_add_f32_e32 v0, v0, v74
	v_add_f32_e32 v164, v164, v75
	s_waitcnt lgkmcnt(14)
	v_add_f32_e32 v0, v0, v76
	v_add_f32_e32 v164, v164, v77
	s_waitcnt lgkmcnt(13)
	v_add_f32_e32 v0, v0, v78
	v_add_f32_e32 v164, v164, v79
	s_waitcnt lgkmcnt(12)
	v_add_f32_e32 v0, v0, v80
	v_add_f32_e32 v164, v164, v81
	s_waitcnt lgkmcnt(11)
	v_add_f32_e32 v0, v0, v82
	v_add_f32_e32 v164, v164, v83
	s_waitcnt lgkmcnt(10)
	v_add_f32_e32 v0, v0, v84
	v_add_f32_e32 v164, v164, v85
	s_waitcnt lgkmcnt(9)
	v_add_f32_e32 v0, v0, v86
	v_add_f32_e32 v164, v164, v87
	s_waitcnt lgkmcnt(8)
	v_add_f32_e32 v0, v0, v88
	v_add_f32_e32 v164, v164, v89
	s_waitcnt lgkmcnt(7)
	v_add_f32_e32 v0, v0, v90
	v_add_f32_e32 v164, v164, v91
	s_waitcnt lgkmcnt(6)
	v_add_f32_e32 v0, v0, v92
	v_add_f32_e32 v164, v164, v93
	s_waitcnt lgkmcnt(5)
	v_add_f32_e32 v0, v0, v94
	v_add_f32_e32 v164, v164, v95
	s_waitcnt lgkmcnt(4)
	v_add_f32_e32 v0, v0, v96
	v_add_f32_e32 v164, v164, v97
	s_waitcnt lgkmcnt(3)
	v_add_f32_e32 v0, v0, v228
	v_add_f32_e32 v164, v164, v229
	s_waitcnt lgkmcnt(2)
	v_add_f32_e32 v0, v0, v230
	v_add_f32_e32 v164, v164, v231
	s_waitcnt lgkmcnt(1)
	v_add_f32_e32 v0, v0, v232
	v_add_f32_e32 v164, v164, v233
	s_waitcnt lgkmcnt(0)
	v_add_f32_e32 v0, v0, v234
	v_mul_f32_e32 v162, 0x3a800000, v0
	v_add_f32_e32 v163, v164, v235
	v_mul_f32_e32 v0, v162, v162
	v_fma_f32 v0, v163, s26, -v0
	v_max_f32_e32 v0, 0, v0
	v_add_f32_e32 v0, 0x358637bd, v0
	v_rsq_f32_e32 v163, v0
	ds_write_b64 v141, v[162:163]
	s_branch .LBB0_1209
